# v45 plus the 64 workgroups idle in the P1 sample-row part convert tiles 0-7 (of 18 per wave) of 64 conversion units there; P2 continues those units at tile 8
# baseline (speedup 1.0000x reference)
.LBB0_219:
	s_waitcnt lgkmcnt(0)
	v_or_b32_e32 v2, 27, v36
	v_bfe_u32 v3, v17, 16, 1
	v_add3_u32 v8, v17, v3, s42
	v_ashrrev_i32_e32 v3, 31, v2
	v_lshlrev_b64 v[2:3], 11, v[2:3]
	v_or_b32_e32 v2, v2, v34
	v_lshlrev_b64 v[4:5], 1, v[2:3]
	v_lshl_add_u64 v[6:7], s[74:75], 0, v[4:5]
	global_store_short_d16_hi v[6:7], v8, off
	v_bfe_u32 v6, v33, 16, 1
	v_or_b32_e32 v4, 64, v4
	v_add3_u32 v6, v33, v6, s42
	v_lshl_add_u64 v[4:5], s[74:75], 0, v[4:5]
	s_and_b64 vcc, exec, s[8:9]
	global_store_short_d16_hi v[4:5], v6, off
	s_cbranch_vccnz .LBB0_145
	v_lshl_add_u64 v[2:3], v[2:3], 2, s[72:73]
	global_store_dword v[2:3], v17, off
	global_store_dword v[2:3], v33, off offset:128
	s_branch .LBB0_145
	s_branch .LBB0_221
.Lp1cv:
	s_add_i32 s2, s96, 0xffffff40
	s_cmp_ge_u32 s2, 64
	s_cbranch_scc1 .LBB0_221
	s_waitcnt vmcnt(0)
	s_barrier
	s_and_b32 s4, s2, 7
	s_lshl_b32 s4, s4, 5
	s_lshr_b32 s2, s2, 3
	s_add_i32 s2, s2, s4
	s_mul_i32 s2, s2, 0x90
	s_add_i32 s2, s2, s76
	s_add_i32 s60, s2, 56
	s_load_dwordx2 s[52:53], s[0:1], 0x70
	s_load_dwordx2 s[54:55], s[0:1], 0x80
	s_load_dwordx2 s[56:57], s[0:1], 0x88
	s_load_dwordx2 s[16:17], s[0:1], 0xa0
	v_and_b32_e32 v3, 63, v0
	v_lshrrev_b32_e32 v84, 4, v3
	v_and_b32_e32 v85, 15, v3
	v_lshlrev_b32_e32 v85, 4, v85
	s_mul_i32 s4, s76, 0x2400
	v_mul_u32_u24_e32 v86, 36, v85
	v_lshl_add_u32 v86, v84, 4, v86
	v_add_u32_e32 v86, s4, v86
	v_lshrrev_b32_e32 v87, 3, v3
	v_mul_u32_u24_e32 v87, 0x90, v87
	v_and_b32_e32 v88, 7, v3
	v_lshl_add_u32 v87, v88, 4, v87
	v_add_u32_e32 v87, s4, v87
	v_lshlrev_b32_e32 v88, 4, v3
	s_movk_i32 s41, 4
	s_waitcnt lgkmcnt(0)
	s_mov_b32 s12, s2
	s_mov_b64 s[10:11], s[54:55]
	s_movk_i32 s4, 0x1000
	s_mov_b32 s5, 8
	s_mov_b32 s6, 0x8400000
	s_cmpk_lt_u32 s12, 0x1000
	s_cselect_b64 s[10:11], s[52:53], s[10:11]
	s_cselect_b32 s4, 0, s4
	s_cselect_b32 s5, 6, s5
	s_cselect_b32 s6, 0x6400000, s6
	s_cmpk_lt_u32 s12, 0x5000
	s_cselect_b64 s[10:11], s[10:11], s[56:57]
	s_cselect_b32 s4, s4, 0x5000
	s_cselect_b32 s5, s5, 6
	s_cselect_b32 s6, s6, 0x10400000
	s_cselect_b32 s7, 6, 8
	s_sub_i32 s12, s12, s4
	s_lshr_b32 s4, s12, s5
	s_bfm_b32 s8, s5, 0
	s_and_b32 s12, s12, s8
	s_lshr_b32 s8, s12, 2
	s_lshl_b32 s8, s8, s7
	s_add_i32 s8, s8, s4
	s_lshl_b32 s8, s8, 15
	s_and_b32 s9, s12, 3
	s_lshl_b32 s9, s9, 13
	s_add_i32 s8, s8, s9
	s_add_u32 s8, s8, s6
	s_add_u32 s48, s8, s16
	s_addc_u32 s49, s17, 0
	s_add_i32 s7, s5, 14
	s_lshl_b32 s4, s4, s7
	s_lshl_b32 s12, s12, 8
	s_add_i32 s4, s4, s12
	s_add_u32 s10, s10, s4
	s_addc_u32 s11, s11, 0
	s_add_i32 s7, s5, 8
	s_lshl_b32 s43, 1, s7
	s_mul_i32 s45, s43, 25
	s_lshl_b32 s47, s43, 3
	v_mad_u32_u24 v89, v84, s47, v85
	global_load_dwordx4 v[20:23], v89, s[10:11] nt
	s_add_u32 s10, s10, s43
	s_addc_u32 s11, s11, 0
	global_load_dwordx4 v[24:27], v89, s[10:11] nt
	s_add_u32 s10, s10, s43
	s_addc_u32 s11, s11, 0
	global_load_dwordx4 v[28:31], v89, s[10:11] nt
	s_add_u32 s10, s10, s43
	s_addc_u32 s11, s11, 0
	global_load_dwordx4 v[32:35], v89, s[10:11] nt
	s_add_u32 s10, s10, s43
	s_addc_u32 s11, s11, 0
	global_load_dwordx4 v[36:39], v89, s[10:11] nt
	s_add_u32 s10, s10, s43
	s_addc_u32 s11, s11, 0
	global_load_dwordx4 v[40:43], v89, s[10:11] nt
	s_add_u32 s10, s10, s43
	s_addc_u32 s11, s11, 0
	global_load_dwordx4 v[44:47], v89, s[10:11] nt
	s_add_u32 s10, s10, s43
	s_addc_u32 s11, s11, 0
	global_load_dwordx4 v[48:51], v89, s[10:11] nt
	s_add_u32 s10, s10, s45
	s_addc_u32 s11, s11, 0
	global_load_dwordx4 v[52:55], v89, s[10:11] nt
	s_add_u32 s10, s10, s43
	s_addc_u32 s11, s11, 0
	global_load_dwordx4 v[56:59], v89, s[10:11] nt
	s_add_u32 s10, s10, s43
	s_addc_u32 s11, s11, 0
	global_load_dwordx4 v[60:63], v89, s[10:11] nt
	s_add_u32 s10, s10, s43
	s_addc_u32 s11, s11, 0
	global_load_dwordx4 v[64:67], v89, s[10:11] nt
	s_add_u32 s10, s10, s43
	s_addc_u32 s11, s11, 0
	global_load_dwordx4 v[68:71], v89, s[10:11] nt
	s_add_u32 s10, s10, s43
	s_addc_u32 s11, s11, 0
	global_load_dwordx4 v[72:75], v89, s[10:11] nt
	s_add_u32 s10, s10, s43
	s_addc_u32 s11, s11, 0
	global_load_dwordx4 v[76:79], v89, s[10:11] nt
	s_add_u32 s10, s10, s43
	s_addc_u32 s11, s11, 0
	global_load_dwordx4 v[80:83], v89, s[10:11] nt
.Lp1cv_loop:
	s_mov_b64 s[50:51], s[48:49]
	s_add_i32 s2, s2, 8
	s_min_u32 s12, s2, s60
	s_mov_b64 s[10:11], s[54:55]
	s_movk_i32 s4, 0x1000
	s_mov_b32 s5, 8
	s_mov_b32 s6, 0x8400000
	s_cmpk_lt_u32 s12, 0x1000
	s_cselect_b64 s[10:11], s[52:53], s[10:11]
	s_cselect_b32 s4, 0, s4
	s_cselect_b32 s5, 6, s5
	s_cselect_b32 s6, 0x6400000, s6
	s_cmpk_lt_u32 s12, 0x5000
	s_cselect_b64 s[10:11], s[10:11], s[56:57]
	s_cselect_b32 s4, s4, 0x5000
	s_cselect_b32 s5, s5, 6
	s_cselect_b32 s6, s6, 0x10400000
	s_cselect_b32 s7, 6, 8
	s_sub_i32 s12, s12, s4
	s_lshr_b32 s4, s12, s5
	s_bfm_b32 s8, s5, 0
	s_and_b32 s12, s12, s8
	s_lshr_b32 s8, s12, 2
	s_lshl_b32 s8, s8, s7
	s_add_i32 s8, s8, s4
	s_lshl_b32 s8, s8, 15
	s_and_b32 s9, s12, 3
	s_lshl_b32 s9, s9, 13
	s_add_i32 s8, s8, s9
	s_add_u32 s8, s8, s6
	s_add_u32 s48, s8, s16
	s_addc_u32 s49, s17, 0
	s_add_i32 s7, s5, 14
	s_lshl_b32 s4, s4, s7
	s_lshl_b32 s12, s12, 8
	s_add_i32 s4, s4, s12
	s_add_u32 s10, s10, s4
	s_addc_u32 s11, s11, 0
	s_add_i32 s7, s5, 8
	s_lshl_b32 s43, 1, s7
	s_mul_i32 s45, s43, 25
	s_lshl_b32 s47, s43, 3
	v_mad_u32_u24 v89, v84, s47, v85
	global_load_dwordx4 v[100:103], v89, s[10:11] nt
	s_add_u32 s10, s10, s43
	s_addc_u32 s11, s11, 0
	global_load_dwordx4 v[104:107], v89, s[10:11] nt
	s_add_u32 s10, s10, s43
	s_addc_u32 s11, s11, 0
	global_load_dwordx4 v[108:111], v89, s[10:11] nt
	s_add_u32 s10, s10, s43
	s_addc_u32 s11, s11, 0
	global_load_dwordx4 v[112:115], v89, s[10:11] nt
	s_add_u32 s10, s10, s43
	s_addc_u32 s11, s11, 0
	global_load_dwordx4 v[116:119], v89, s[10:11] nt
	s_add_u32 s10, s10, s43
	s_addc_u32 s11, s11, 0
	global_load_dwordx4 v[120:123], v89, s[10:11] nt
	s_add_u32 s10, s10, s43
	s_addc_u32 s11, s11, 0
	global_load_dwordx4 v[124:127], v89, s[10:11] nt
	s_add_u32 s10, s10, s43
	s_addc_u32 s11, s11, 0
	global_load_dwordx4 v[128:131], v89, s[10:11] nt
	s_add_u32 s10, s10, s45
	s_addc_u32 s11, s11, 0
	global_load_dwordx4 v[132:135], v89, s[10:11] nt
	s_add_u32 s10, s10, s43
	s_addc_u32 s11, s11, 0
	global_load_dwordx4 v[136:139], v89, s[10:11] nt
	s_add_u32 s10, s10, s43
	s_addc_u32 s11, s11, 0
	global_load_dwordx4 v[140:143], v89, s[10:11] nt
	s_add_u32 s10, s10, s43
	s_addc_u32 s11, s11, 0
	global_load_dwordx4 v[144:147], v89, s[10:11] nt
	s_add_u32 s10, s10, s43
	s_addc_u32 s11, s11, 0
	global_load_dwordx4 v[148:151], v89, s[10:11] nt
	s_add_u32 s10, s10, s43
	s_addc_u32 s11, s11, 0
	global_load_dwordx4 v[152:155], v89, s[10:11] nt
	s_add_u32 s10, s10, s43
	s_addc_u32 s11, s11, 0
	global_load_dwordx4 v[156:159], v89, s[10:11] nt
	s_add_u32 s10, s10, s43
	s_addc_u32 s11, s11, 0
	global_load_dwordx4 v[160:163], v89, s[10:11] nt
	s_waitcnt vmcnt(16)
	v_cvt_pk_bf16_f32 v164, v20, v24
	v_cvt_pk_bf16_f32 v165, v28, v32
	v_cvt_pk_bf16_f32 v166, v36, v40
	v_cvt_pk_bf16_f32 v167, v44, v48
	ds_write_b128 v86, v[164:167]
	v_cvt_pk_bf16_f32 v168, v21, v25
	v_cvt_pk_bf16_f32 v169, v29, v33
	v_cvt_pk_bf16_f32 v170, v37, v41
	v_cvt_pk_bf16_f32 v171, v45, v49
	ds_write_b128 v86, v[168:171] offset:144
	v_cvt_pk_bf16_f32 v172, v22, v26
	v_cvt_pk_bf16_f32 v173, v30, v34
	v_cvt_pk_bf16_f32 v174, v38, v42
	v_cvt_pk_bf16_f32 v175, v46, v50
	ds_write_b128 v86, v[172:175] offset:288
	v_cvt_pk_bf16_f32 v176, v23, v27
	v_cvt_pk_bf16_f32 v177, v31, v35
	v_cvt_pk_bf16_f32 v178, v39, v43
	v_cvt_pk_bf16_f32 v179, v47, v51
	ds_write_b128 v86, v[176:179] offset:432
	v_cvt_pk_bf16_f32 v180, v52, v56
	v_cvt_pk_bf16_f32 v181, v60, v64
	v_cvt_pk_bf16_f32 v182, v68, v72
	v_cvt_pk_bf16_f32 v183, v76, v80
	ds_write_b128 v86, v[180:183] offset:64
	v_cvt_pk_bf16_f32 v184, v53, v57
	v_cvt_pk_bf16_f32 v185, v61, v65
	v_cvt_pk_bf16_f32 v186, v69, v73
	v_cvt_pk_bf16_f32 v187, v77, v81
	ds_write_b128 v86, v[184:187] offset:208
	v_cvt_pk_bf16_f32 v188, v54, v58
	v_cvt_pk_bf16_f32 v189, v62, v66
	v_cvt_pk_bf16_f32 v190, v70, v74
	v_cvt_pk_bf16_f32 v191, v78, v82
	ds_write_b128 v86, v[188:191] offset:352
	v_cvt_pk_bf16_f32 v192, v55, v59
	v_cvt_pk_bf16_f32 v193, v63, v67
	v_cvt_pk_bf16_f32 v194, v71, v75
	v_cvt_pk_bf16_f32 v195, v79, v83
	ds_write_b128 v86, v[192:195] offset:496
	s_add_u32 s8, s50, 0x1000
	s_addc_u32 s9, s51, 0
	s_waitcnt lgkmcnt(0)
	ds_read_b128 v[164:167], v87
	ds_read_b128 v[168:171], v87 offset:1152
	ds_read_b128 v[172:175], v87 offset:2304
	ds_read_b128 v[176:179], v87 offset:3456
	ds_read_b128 v[180:183], v87 offset:4608
	ds_read_b128 v[184:187], v87 offset:5760
	ds_read_b128 v[188:191], v87 offset:6912
	ds_read_b128 v[192:195], v87 offset:8064
	s_waitcnt lgkmcnt(7)
	global_store_dwordx4 v88, v[164:167], s[50:51] nt
	s_waitcnt lgkmcnt(6)
	global_store_dwordx4 v88, v[168:171], s[50:51] offset:1024 nt
	s_waitcnt lgkmcnt(5)
	global_store_dwordx4 v88, v[172:175], s[50:51] offset:2048 nt
	s_waitcnt lgkmcnt(4)
	global_store_dwordx4 v88, v[176:179], s[50:51] offset:3072 nt
	s_waitcnt lgkmcnt(3)
	global_store_dwordx4 v88, v[180:183], s[8:9] nt
	s_waitcnt lgkmcnt(2)
	global_store_dwordx4 v88, v[184:187], s[8:9] offset:1024 nt
	s_waitcnt lgkmcnt(1)
	global_store_dwordx4 v88, v[188:191], s[8:9] offset:2048 nt
	s_waitcnt lgkmcnt(0)
	global_store_dwordx4 v88, v[192:195], s[8:9] offset:3072 nt
	s_mov_b64 s[50:51], s[48:49]
	s_add_i32 s2, s2, 8
	s_min_u32 s12, s2, s60
	s_mov_b64 s[10:11], s[54:55]
	s_movk_i32 s4, 0x1000
	s_mov_b32 s5, 8
	s_mov_b32 s6, 0x8400000
	s_cmpk_lt_u32 s12, 0x1000
	s_cselect_b64 s[10:11], s[52:53], s[10:11]
	s_cselect_b32 s4, 0, s4
	s_cselect_b32 s5, 6, s5
	s_cselect_b32 s6, 0x6400000, s6
	s_cmpk_lt_u32 s12, 0x5000
	s_cselect_b64 s[10:11], s[10:11], s[56:57]
	s_cselect_b32 s4, s4, 0x5000
	s_cselect_b32 s5, s5, 6
	s_cselect_b32 s6, s6, 0x10400000
	s_cselect_b32 s7, 6, 8
	s_sub_i32 s12, s12, s4
	s_lshr_b32 s4, s12, s5
	s_bfm_b32 s8, s5, 0
	s_and_b32 s12, s12, s8
	s_lshr_b32 s8, s12, 2
	s_lshl_b32 s8, s8, s7
	s_add_i32 s8, s8, s4
	s_lshl_b32 s8, s8, 15
	s_and_b32 s9, s12, 3
	s_lshl_b32 s9, s9, 13
	s_add_i32 s8, s8, s9
	s_add_u32 s8, s8, s6
	s_add_u32 s48, s8, s16
	s_addc_u32 s49, s17, 0
	s_add_i32 s7, s5, 14
	s_lshl_b32 s4, s4, s7
	s_lshl_b32 s12, s12, 8
	s_add_i32 s4, s4, s12
	s_add_u32 s10, s10, s4
	s_addc_u32 s11, s11, 0
	s_add_i32 s7, s5, 8
	s_lshl_b32 s43, 1, s7
	s_mul_i32 s45, s43, 25
	s_lshl_b32 s47, s43, 3
	v_mad_u32_u24 v89, v84, s47, v85
	global_load_dwordx4 v[20:23], v89, s[10:11] nt
	s_add_u32 s10, s10, s43
	s_addc_u32 s11, s11, 0
	global_load_dwordx4 v[24:27], v89, s[10:11] nt
	s_add_u32 s10, s10, s43
	s_addc_u32 s11, s11, 0
	global_load_dwordx4 v[28:31], v89, s[10:11] nt
	s_add_u32 s10, s10, s43
	s_addc_u32 s11, s11, 0
	global_load_dwordx4 v[32:35], v89, s[10:11] nt
	s_add_u32 s10, s10, s43
	s_addc_u32 s11, s11, 0
	global_load_dwordx4 v[36:39], v89, s[10:11] nt
	s_add_u32 s10, s10, s43
	s_addc_u32 s11, s11, 0
	global_load_dwordx4 v[40:43], v89, s[10:11] nt
	s_add_u32 s10, s10, s43
	s_addc_u32 s11, s11, 0
	global_load_dwordx4 v[44:47], v89, s[10:11] nt
	s_add_u32 s10, s10, s43
	s_addc_u32 s11, s11, 0
	global_load_dwordx4 v[48:51], v89, s[10:11] nt
	s_add_u32 s10, s10, s45
	s_addc_u32 s11, s11, 0
	global_load_dwordx4 v[52:55], v89, s[10:11] nt
	s_add_u32 s10, s10, s43
	s_addc_u32 s11, s11, 0
	global_load_dwordx4 v[56:59], v89, s[10:11] nt
	s_add_u32 s10, s10, s43
	s_addc_u32 s11, s11, 0
	global_load_dwordx4 v[60:63], v89, s[10:11] nt
	s_add_u32 s10, s10, s43
	s_addc_u32 s11, s11, 0
	global_load_dwordx4 v[64:67], v89, s[10:11] nt
	s_add_u32 s10, s10, s43
	s_addc_u32 s11, s11, 0
	global_load_dwordx4 v[68:71], v89, s[10:11] nt
	s_add_u32 s10, s10, s43
	s_addc_u32 s11, s11, 0
	global_load_dwordx4 v[72:75], v89, s[10:11] nt
	s_add_u32 s10, s10, s43
	s_addc_u32 s11, s11, 0
	global_load_dwordx4 v[76:79], v89, s[10:11] nt
	s_add_u32 s10, s10, s43
	s_addc_u32 s11, s11, 0
	global_load_dwordx4 v[80:83], v89, s[10:11] nt
	s_waitcnt vmcnt(16)
	v_cvt_pk_bf16_f32 v164, v100, v104
	v_cvt_pk_bf16_f32 v165, v108, v112
	v_cvt_pk_bf16_f32 v166, v116, v120
	v_cvt_pk_bf16_f32 v167, v124, v128
	ds_write_b128 v86, v[164:167]
	v_cvt_pk_bf16_f32 v168, v101, v105
	v_cvt_pk_bf16_f32 v169, v109, v113
	v_cvt_pk_bf16_f32 v170, v117, v121
	v_cvt_pk_bf16_f32 v171, v125, v129
	ds_write_b128 v86, v[168:171] offset:144
	v_cvt_pk_bf16_f32 v172, v102, v106
	v_cvt_pk_bf16_f32 v173, v110, v114
	v_cvt_pk_bf16_f32 v174, v118, v122
	v_cvt_pk_bf16_f32 v175, v126, v130
	ds_write_b128 v86, v[172:175] offset:288
	v_cvt_pk_bf16_f32 v176, v103, v107
	v_cvt_pk_bf16_f32 v177, v111, v115
	v_cvt_pk_bf16_f32 v178, v119, v123
	v_cvt_pk_bf16_f32 v179, v127, v131
	ds_write_b128 v86, v[176:179] offset:432
	v_cvt_pk_bf16_f32 v180, v132, v136
	v_cvt_pk_bf16_f32 v181, v140, v144
	v_cvt_pk_bf16_f32 v182, v148, v152
	v_cvt_pk_bf16_f32 v183, v156, v160
	ds_write_b128 v86, v[180:183] offset:64
	v_cvt_pk_bf16_f32 v184, v133, v137
	v_cvt_pk_bf16_f32 v185, v141, v145
	v_cvt_pk_bf16_f32 v186, v149, v153
	v_cvt_pk_bf16_f32 v187, v157, v161
	ds_write_b128 v86, v[184:187] offset:208
	v_cvt_pk_bf16_f32 v188, v134, v138
	v_cvt_pk_bf16_f32 v189, v142, v146
	v_cvt_pk_bf16_f32 v190, v150, v154
	v_cvt_pk_bf16_f32 v191, v158, v162
	ds_write_b128 v86, v[188:191] offset:352
	v_cvt_pk_bf16_f32 v192, v135, v139
	v_cvt_pk_bf16_f32 v193, v143, v147
	v_cvt_pk_bf16_f32 v194, v151, v155
	v_cvt_pk_bf16_f32 v195, v159, v163
	ds_write_b128 v86, v[192:195] offset:496
	s_add_u32 s8, s50, 0x1000
	s_addc_u32 s9, s51, 0
	s_waitcnt lgkmcnt(0)
	ds_read_b128 v[164:167], v87
	ds_read_b128 v[168:171], v87 offset:1152
	ds_read_b128 v[172:175], v87 offset:2304
	ds_read_b128 v[176:179], v87 offset:3456
	ds_read_b128 v[180:183], v87 offset:4608
	ds_read_b128 v[184:187], v87 offset:5760
	ds_read_b128 v[188:191], v87 offset:6912
	ds_read_b128 v[192:195], v87 offset:8064
	s_waitcnt lgkmcnt(7)
	global_store_dwordx4 v88, v[164:167], s[50:51] nt
	s_waitcnt lgkmcnt(6)
	global_store_dwordx4 v88, v[168:171], s[50:51] offset:1024 nt
	s_waitcnt lgkmcnt(5)
	global_store_dwordx4 v88, v[172:175], s[50:51] offset:2048 nt
	s_waitcnt lgkmcnt(4)
	global_store_dwordx4 v88, v[176:179], s[50:51] offset:3072 nt
	s_waitcnt lgkmcnt(3)
	global_store_dwordx4 v88, v[180:183], s[8:9] nt
	s_waitcnt lgkmcnt(2)
	global_store_dwordx4 v88, v[184:187], s[8:9] offset:1024 nt
	s_waitcnt lgkmcnt(1)
	global_store_dwordx4 v88, v[188:191], s[8:9] offset:2048 nt
	s_waitcnt lgkmcnt(0)
	global_store_dwordx4 v88, v[192:195], s[8:9] offset:3072 nt
	s_add_i32 s41, s41, -1
	s_cmp_lg_u32 s41, 0
	s_cbranch_scc1 .Lp1cv_loop
	s_waitcnt vmcnt(0)
	s_branch .LBB0_221

.LBB0_357:
	s_andn2_b64 vcc, exec, s[14:15]
	s_cbranch_vccnz .LBB0_280
	s_cmp_eq_u32 s2, 6
	s_cselect_b32 s4, 1, 0
	s_lshl_b32 s2, s50, 1
	s_add_i32 s2, s2, s4
	s_cmp_lt_u32 s2, 8
	s_cselect_b32 s5, 64, 0
	s_cselect_b32 s41, 5, 9
	s_add_i32 s2, s2, s89
	s_mul_i32 s2, s2, 0x90
	s_add_i32 s2, s2, s76
	s_add_i32 s86, s2, 0x88
	s_add_i32 s2, s2, s5
	s_load_dwordx2 s[78:79], s[0:1], 0x70
	s_load_dwordx2 s[80:81], s[0:1], 0x80
	s_load_dwordx2 s[82:83], s[0:1], 0x88
	s_load_dwordx2 s[16:17], s[0:1], 0xa0
	v_and_b32_e32 v3, 63, v0
	v_lshrrev_b32_e32 v84, 4, v3
	v_and_b32_e32 v85, 15, v3
	v_lshlrev_b32_e32 v85, 4, v85
	s_mul_i32 s4, s76, 0x2400
	v_mul_u32_u24_e32 v86, 36, v85
	v_lshl_add_u32 v86, v84, 4, v86
	v_add_u32_e32 v86, s4, v86
	v_lshrrev_b32_e32 v87, 3, v3
	v_mul_u32_u24_e32 v87, 0x90, v87
	v_and_b32_e32 v88, 7, v3
	v_lshl_add_u32 v87, v88, 4, v87
	v_add_u32_e32 v87, s4, v87
	v_lshlrev_b32_e32 v88, 4, v3
	s_waitcnt lgkmcnt(0)
	s_mov_b32 s12, s2
	s_mov_b64 s[10:11], s[80:81]
	s_movk_i32 s4, 0x1000
	s_mov_b32 s5, 8
	s_mov_b32 s6, 0x8400000
	s_cmpk_lt_u32 s12, 0x1000
	s_cselect_b64 s[10:11], s[78:79], s[10:11]
	s_cselect_b32 s4, 0, s4
	s_cselect_b32 s5, 6, s5
	s_cselect_b32 s6, 0x6400000, s6
	s_cmpk_lt_u32 s12, 0x5000
	s_cselect_b64 s[10:11], s[10:11], s[82:83]
	s_cselect_b32 s4, s4, 0x5000
	s_cselect_b32 s5, s5, 6
	s_cselect_b32 s6, s6, 0x10400000
	s_cselect_b32 s7, 6, 8
	s_sub_i32 s12, s12, s4
	s_lshr_b32 s4, s12, s5
	s_bfm_b32 s8, s5, 0
	s_and_b32 s12, s12, s8
	s_lshr_b32 s8, s12, 2
	s_lshl_b32 s8, s8, s7
	s_add_i32 s8, s8, s4
	s_lshl_b32 s8, s8, 15
	s_and_b32 s9, s12, 3
	s_lshl_b32 s9, s9, 13
	s_add_i32 s8, s8, s9
	s_add_u32 s8, s8, s6
	s_add_u32 s48, s8, s16
	s_addc_u32 s49, s17, 0
	s_add_i32 s7, s5, 14
	s_lshl_b32 s4, s4, s7
	s_lshl_b32 s12, s12, 8
	s_add_i32 s4, s4, s12
	s_add_u32 s10, s10, s4
	s_addc_u32 s11, s11, 0
	s_add_i32 s7, s5, 8
	s_lshl_b32 s43, 1, s7
	s_mul_i32 s45, s43, 25
	s_lshl_b32 s47, s43, 3
	v_mad_u32_u24 v89, v84, s47, v85
	global_load_dwordx4 v[20:23], v89, s[10:11] nt
	s_add_u32 s10, s10, s43
	s_addc_u32 s11, s11, 0
	global_load_dwordx4 v[24:27], v89, s[10:11] nt
	s_add_u32 s10, s10, s43
	s_addc_u32 s11, s11, 0
	global_load_dwordx4 v[28:31], v89, s[10:11] nt
	s_add_u32 s10, s10, s43
	s_addc_u32 s11, s11, 0
	global_load_dwordx4 v[32:35], v89, s[10:11] nt
	s_add_u32 s10, s10, s43
	s_addc_u32 s11, s11, 0
	global_load_dwordx4 v[36:39], v89, s[10:11] nt
	s_add_u32 s10, s10, s43
	s_addc_u32 s11, s11, 0
	global_load_dwordx4 v[40:43], v89, s[10:11] nt
	s_add_u32 s10, s10, s43
	s_addc_u32 s11, s11, 0
	global_load_dwordx4 v[44:47], v89, s[10:11] nt
	s_add_u32 s10, s10, s43
	s_addc_u32 s11, s11, 0
	global_load_dwordx4 v[48:51], v89, s[10:11] nt
	s_add_u32 s10, s10, s45
	s_addc_u32 s11, s11, 0
	global_load_dwordx4 v[52:55], v89, s[10:11] nt
	s_add_u32 s10, s10, s43
	s_addc_u32 s11, s11, 0
	global_load_dwordx4 v[56:59], v89, s[10:11] nt
	s_add_u32 s10, s10, s43
	s_addc_u32 s11, s11, 0
	global_load_dwordx4 v[60:63], v89, s[10:11] nt
	s_add_u32 s10, s10, s43
	s_addc_u32 s11, s11, 0
	global_load_dwordx4 v[64:67], v89, s[10:11] nt
	s_add_u32 s10, s10, s43
	s_addc_u32 s11, s11, 0
	global_load_dwordx4 v[68:71], v89, s[10:11] nt
	s_add_u32 s10, s10, s43
	s_addc_u32 s11, s11, 0
	global_load_dwordx4 v[72:75], v89, s[10:11] nt
	s_add_u32 s10, s10, s43
	s_addc_u32 s11, s11, 0
	global_load_dwordx4 v[76:79], v89, s[10:11] nt
	s_add_u32 s10, s10, s43
	s_addc_u32 s11, s11, 0
	global_load_dwordx4 v[80:83], v89, s[10:11] nt
